# init phase weight transposes: next tile requested behind the current tile's loads, counted wait vmcnt(2) so the prefetch stays in flight across the LDS transpose
# baseline (speedup 1.0000x reference)
; DI void transpose_job(const int TID, const int BID, LAS unsigned char* lds, const float* W, int K, int Nsrc, int Npad, bf16_t* Bt, int mode, const float* kscale) {
;     ...
;     for (int t = BID; t < ntile; t += gridDim.x) {
;         const int n0 = (t / nkt) << 6, k0 = (t % nkt) << 6;
;         const int sc = srccol(mode, n0 + 4 * dq);
;         f32x4 va = {0.f, 0.f, 0.f, 0.f}, vb = va;
;         if (sc >= 0) {
;             va = *(const f32x4*)(W + (size_t)(k0 + 2 * kp) * Nsrc + sc); vb = *(const f32x4*)(W + (size_t)(k0 + 2 * kp + 1) * Nsrc + sc);
.LBB0_827:
	v_or_b32_e32 v0, s9, v79
	s_and_b32 s11, s9, 0x7fffff00
	v_lshlrev_b32_e32 v1, 1, v0
	v_lshrrev_b32_e32 v0, 2, v0
	v_and_or_b32 v0, v0, 36, s11
	s_add_i32 s11, s10, s7
	v_add_u32_e32 v2, s11, v11
	v_ashrrev_i32_e32 v3, 31, v2
	v_lshlrev_b64 v[4:5], 14, v[2:3]
	v_add_u32_e32 v2, 1, v2
	v_and_b32_e32 v1, 0xc0, v1
	v_ashrrev_i32_e32 v3, 31, v2
	v_or3_b32 v0, v0, v1, v8
	v_mov_b32_e32 v1, v169
	v_lshlrev_b64 v[2:3], 14, v[2:3]
	v_lshl_add_u64 v[4:5], s[16:17], 0, v[4:5]
	v_lshlrev_b64 v[0:1], 2, v[0:1]
	v_lshl_add_u64 v[2:3], s[16:17], 0, v[2:3]
	v_lshl_add_u64 v[4:5], v[4:5], 0, v[0:1]
	v_lshl_add_u64 v[6:7], v[2:3], 0, v[0:1]
	global_load_dwordx4 v[0:3], v[4:5], off
	s_nop 0
	global_load_dwordx4 v[4:7], v[6:7], off
	v_writelane_b32 v255, s9, 40
	v_writelane_b32 v255, s10, 41
	s_add_i32 s7, s7, s6
	s_add_i32 s8, s8, s4
	s_cmpk_ge_i32 s8, 0x400
	s_cbranch_scc1 .Linitpf_skip_1
	s_ashr_i32 s9, s8, 31
	s_lshr_b32 s9, s9, 28
	s_add_i32 s9, s8, s9
	s_ashr_i32 s10, s9, 4
	s_lshl_b32 s9, s10, 6
	s_lshl_b32 s10, s10, 10
	s_sub_i32 s10, 0, s10
	s_cmp_lt_i32 s9, 0
	s_cbranch_scc1 .Linitpf_skip_1
	v_or_b32_e32 v224, s9, v79
	s_and_b32 s11, s9, 0x7fffff00
	v_lshlrev_b32_e32 v225, 1, v224
	v_lshrrev_b32_e32 v224, 2, v224
	v_and_or_b32 v224, v224, 36, s11
	s_add_i32 s11, s10, s7
	v_add_u32_e32 v226, s11, v11
	v_ashrrev_i32_e32 v227, 31, v226
	v_lshlrev_b64 v[228:229], 14, v[226:227]
	v_add_u32_e32 v226, 1, v226
	v_and_b32_e32 v225, 0xc0, v225
	v_ashrrev_i32_e32 v227, 31, v226
	v_or3_b32 v224, v224, v225, v8
	v_mov_b32_e32 v225, v169
	v_lshlrev_b64 v[226:227], 14, v[226:227]
	v_lshl_add_u64 v[228:229], s[16:17], 0, v[228:229]
	v_lshlrev_b64 v[224:225], 2, v[224:225]
	v_lshl_add_u64 v[226:227], s[16:17], 0, v[226:227]
	v_lshl_add_u64 v[228:229], v[228:229], 0, v[224:225]
	v_lshl_add_u64 v[230:231], v[226:227], 0, v[224:225]
	global_load_dwordx4 v[232:235], v[228:229], off
	s_nop 0
	global_load_dwordx4 v[236:239], v[230:231], off
	s_waitcnt vmcnt(2)
	s_branch .Linitpf_join_1

; DI void transpose_job(const int TID, const int BID, LAS unsigned char* lds, const float* W, int K, int Nsrc, int Npad, bf16_t* Bt, int mode, const float* kscale) {
;     ...
; #pragma unroll
;         for (int e = 0; e < 4; ++e) tl[(4 * dq + e) * 33 + kp] = pk_bf16(va[e], vb[e]);
;         __syncthreads();
;         {
;             const int n2 = tid >> 3, c2 = tid & 7;
;             u32x4 o;
; #pragma unroll
;             for (int i = 0; i < 4; ++i) o[i] = tl[n2 * 33 + c2 * 4 + i];
;             *(u32x4*)(Bt + (size_t)(n0 + n2) * K + k0 + c2 * 8) = o;
;         }
;         __syncthreads();
.Linitpf_join_1:
	s_sub_i32 s7, s7, s6
	s_sub_i32 s8, s8, s4
	v_readlane_b32 s9, v255, 40
	v_readlane_b32 s10, v255, 41
.LBB0_828:
	s_waitcnt vmcnt(2)
	v_cvt_pk_bf16_f32 v0, v0, v4
	v_cvt_pk_bf16_f32 v1, v1, v5
	ds_write2_b32 v9, v0, v1 offset1:33
	v_cvt_pk_bf16_f32 v0, v2, v6
	v_cvt_pk_bf16_f32 v1, v3, v7
	v_add_u32_e32 v4, s9, v13
	ds_write2_b32 v9, v0, v1 offset0:66 offset1:99
	s_waitcnt lgkmcnt(0)
	s_barrier
	ds_read2_b32 v[0:1], v17 offset1:1
	ds_read2_b32 v[2:3], v17 offset0:2 offset1:3
	v_ashrrev_i32_e32 v5, 31, v4
	s_add_i32 s10, s7, s10
	v_lshlrev_b64 v[4:5], 11, v[4:5]
	v_lshl_add_u64 v[4:5], s[18:19], 0, v[4:5]
	s_ashr_i32 s11, s10, 31
	v_lshl_add_u64 v[4:5], s[10:11], 1, v[4:5]
	s_add_i32 s8, s8, s4
	s_add_i32 s7, s7, s6
	v_lshl_add_u64 v[4:5], v[4:5], 0, v[168:169]
	s_cmpk_lt_i32 s8, 0x400
	s_waitcnt lgkmcnt(0)
	global_store_dwordx4 v[4:5], v[0:3], off
	s_barrier
	s_cbranch_scc0 .LBB0_831

; DI void transpose_job(const int TID, const int BID, LAS unsigned char* lds, const float* W, int K, int Nsrc, int Npad, bf16_t* Bt, int mode, const float* kscale) {
;     ...
;     for (int t = BID; t < ntile; t += gridDim.x) {
;         const int n0 = (t / nkt) << 6, k0 = (t % nkt) << 6;
;         const int sc = srccol(mode, n0 + 4 * dq);
;         f32x4 va = {0.f, 0.f, 0.f, 0.f}, vb = va;
;         if (sc >= 0) {
;             va = *(const f32x4*)(W + (size_t)(k0 + 2 * kp) * Nsrc + sc); vb = *(const f32x4*)(W + (size_t)(k0 + 2 * kp + 1) * Nsrc + sc);
.LBB0_832:
	v_or_b32_e32 v0, s9, v79
	s_and_b32 s11, s9, 0x7fffff00
	v_lshlrev_b32_e32 v1, 1, v0
	v_lshrrev_b32_e32 v0, 2, v0
	v_and_or_b32 v0, v0, 36, s11
	s_add_i32 s11, s10, s7
	v_add_u32_e32 v2, s11, v11
	v_ashrrev_i32_e32 v3, 31, v2
	v_lshlrev_b64 v[4:5], 14, v[2:3]
	v_add_u32_e32 v2, 1, v2
	v_and_b32_e32 v1, 0xc0, v1
	v_ashrrev_i32_e32 v3, 31, v2
	v_or3_b32 v0, v0, v1, v8
	v_mov_b32_e32 v1, v169
	v_lshlrev_b64 v[2:3], 14, v[2:3]
	v_lshl_add_u64 v[4:5], s[20:21], 0, v[4:5]
	v_lshlrev_b64 v[0:1], 2, v[0:1]
	v_lshl_add_u64 v[2:3], s[20:21], 0, v[2:3]
	v_lshl_add_u64 v[4:5], v[4:5], 0, v[0:1]
	v_lshl_add_u64 v[6:7], v[2:3], 0, v[0:1]
	global_load_dwordx4 v[0:3], v[4:5], off
	s_nop 0
	global_load_dwordx4 v[4:7], v[6:7], off
	v_writelane_b32 v255, s9, 40
	v_writelane_b32 v255, s10, 41
	s_add_i32 s7, s7, s6
	s_add_i32 s8, s8, s4
	s_cmpk_ge_i32 s8, 0x400
	s_cbranch_scc1 .Linitpf_skip_2
	s_ashr_i32 s9, s8, 31
	s_lshr_b32 s9, s9, 28
	s_add_i32 s9, s8, s9
	s_ashr_i32 s10, s9, 4
	s_lshl_b32 s9, s10, 6
	s_lshl_b32 s10, s10, 10
	s_sub_i32 s10, 0, s10
	s_cmp_lt_i32 s9, 0
	s_cbranch_scc1 .Linitpf_skip_2
	v_or_b32_e32 v224, s9, v79
	s_and_b32 s11, s9, 0x7fffff00
	v_lshlrev_b32_e32 v225, 1, v224
	v_lshrrev_b32_e32 v224, 2, v224
	v_and_or_b32 v224, v224, 36, s11
	s_add_i32 s11, s10, s7
	v_add_u32_e32 v226, s11, v11
	v_ashrrev_i32_e32 v227, 31, v226
	v_lshlrev_b64 v[228:229], 14, v[226:227]
	v_add_u32_e32 v226, 1, v226
	v_and_b32_e32 v225, 0xc0, v225
	v_ashrrev_i32_e32 v227, 31, v226
	v_or3_b32 v224, v224, v225, v8
	v_mov_b32_e32 v225, v169
	v_lshlrev_b64 v[226:227], 14, v[226:227]
	v_lshl_add_u64 v[228:229], s[20:21], 0, v[228:229]
	v_lshlrev_b64 v[224:225], 2, v[224:225]
	v_lshl_add_u64 v[226:227], s[20:21], 0, v[226:227]
	v_lshl_add_u64 v[228:229], v[228:229], 0, v[224:225]
	v_lshl_add_u64 v[230:231], v[226:227], 0, v[224:225]
	global_load_dwordx4 v[232:235], v[228:229], off
	s_nop 0
	global_load_dwordx4 v[236:239], v[230:231], off
	s_waitcnt vmcnt(2)
	s_branch .Linitpf_join_2

; DI void transpose_job(const int TID, const int BID, LAS unsigned char* lds, const float* W, int K, int Nsrc, int Npad, bf16_t* Bt, int mode, const float* kscale) {
;     ...
; #pragma unroll
;         for (int e = 0; e < 4; ++e) tl[(4 * dq + e) * 33 + kp] = pk_bf16(va[e], vb[e]);
;         __syncthreads();
;         {
;             const int n2 = tid >> 3, c2 = tid & 7;
;             u32x4 o;
; #pragma unroll
;             for (int i = 0; i < 4; ++i) o[i] = tl[n2 * 33 + c2 * 4 + i];
;             *(u32x4*)(Bt + (size_t)(n0 + n2) * K + k0 + c2 * 8) = o;
;         }
;         __syncthreads();
.LBB0_833:
	s_waitcnt vmcnt(2)
	v_cvt_pk_bf16_f32 v0, v0, v4
	v_cvt_pk_bf16_f32 v1, v1, v5
	ds_write2_b32 v9, v0, v1 offset1:33
	v_cvt_pk_bf16_f32 v0, v2, v6
	v_cvt_pk_bf16_f32 v1, v3, v7
	v_add_u32_e32 v4, s9, v13
	ds_write2_b32 v9, v0, v1 offset0:66 offset1:99
	s_waitcnt lgkmcnt(0)
	s_barrier
	ds_read2_b32 v[0:1], v17 offset1:1
	ds_read2_b32 v[2:3], v17 offset0:2 offset1:3
	v_ashrrev_i32_e32 v5, 31, v4
	s_add_i32 s10, s7, s10
	v_lshlrev_b64 v[4:5], 11, v[4:5]
	v_lshl_add_u64 v[4:5], s[22:23], 0, v[4:5]
	s_ashr_i32 s11, s10, 31
	v_lshl_add_u64 v[4:5], s[10:11], 1, v[4:5]
	s_add_i32 s8, s8, s4
	s_add_i32 s7, s7, s6
	v_lshl_add_u64 v[4:5], v[4:5], 0, v[168:169]
	s_cmpk_lt_i32 s8, 0x400
	s_waitcnt lgkmcnt(0)
	global_store_dwordx4 v[4:5], v[0:3], off
	s_barrier
	s_cbranch_scc0 .LBB0_836

; DI void transpose_job(const int TID, const int BID, LAS unsigned char* lds, const float* W, int K, int Nsrc, int Npad, bf16_t* Bt, int mode, const float* kscale) {
;     ...
;     for (int t = BID; t < ntile; t += gridDim.x) {
;         const int n0 = (t / nkt) << 6, k0 = (t % nkt) << 6;
;         const int sc = srccol(mode, n0 + 4 * dq);
;         f32x4 va = {0.f, 0.f, 0.f, 0.f}, vb = va;
;         if (sc >= 0) {
;             va = *(const f32x4*)(W + (size_t)(k0 + 2 * kp) * Nsrc + sc); vb = *(const f32x4*)(W + (size_t)(k0 + 2 * kp + 1) * Nsrc + sc);
.LBB0_837:
	v_or_b32_e32 v0, s8, v79
	s_and_b32 s10, s8, 0x7fffff00
	v_lshlrev_b32_e32 v1, 1, v0
	v_lshrrev_b32_e32 v0, 2, v0
	v_and_or_b32 v0, v0, 36, s10
	s_add_i32 s10, s9, s5
	v_add_u32_e32 v2, s10, v11
	v_ashrrev_i32_e32 v3, 31, v2
	v_lshlrev_b64 v[4:5], 14, v[2:3]
	v_add_u32_e32 v2, 1, v2
	v_and_b32_e32 v1, 0xc0, v1
	v_ashrrev_i32_e32 v3, 31, v2
	v_or3_b32 v0, v0, v1, v8
	v_mov_b32_e32 v1, v169
	v_lshlrev_b64 v[2:3], 14, v[2:3]
	v_lshl_add_u64 v[4:5], s[12:13], 0, v[4:5]
	v_lshlrev_b64 v[0:1], 2, v[0:1]
	v_lshl_add_u64 v[2:3], s[12:13], 0, v[2:3]
	v_lshl_add_u64 v[4:5], v[4:5], 0, v[0:1]
	v_lshl_add_u64 v[6:7], v[2:3], 0, v[0:1]
	global_load_dwordx4 v[0:3], v[4:5], off
	s_nop 0
	global_load_dwordx4 v[4:7], v[6:7], off
	v_writelane_b32 v255, s8, 40
	v_writelane_b32 v255, s9, 41
	s_add_i32 s5, s5, s6
	s_add_i32 s7, s7, s4
	s_cmpk_ge_i32 s7, 0x400
	s_cbranch_scc1 .Linitpf_skip_3
	s_ashr_i32 s8, s7, 31
	s_lshr_b32 s8, s8, 28
	s_add_i32 s8, s7, s8
	s_ashr_i32 s9, s8, 4
	s_lshl_b32 s8, s9, 6
	s_lshl_b32 s9, s9, 10
	s_sub_i32 s9, 0, s9
	s_cmp_lt_i32 s8, 0
	s_cbranch_scc1 .Linitpf_skip_3
	v_or_b32_e32 v224, s8, v79
	s_and_b32 s10, s8, 0x7fffff00
	v_lshlrev_b32_e32 v225, 1, v224
	v_lshrrev_b32_e32 v224, 2, v224
	v_and_or_b32 v224, v224, 36, s10
	s_add_i32 s10, s9, s5
	v_add_u32_e32 v226, s10, v11
	v_ashrrev_i32_e32 v227, 31, v226
	v_lshlrev_b64 v[228:229], 14, v[226:227]
	v_add_u32_e32 v226, 1, v226
	v_and_b32_e32 v225, 0xc0, v225
	v_ashrrev_i32_e32 v227, 31, v226
	v_or3_b32 v224, v224, v225, v8
	v_mov_b32_e32 v225, v169
	v_lshlrev_b64 v[226:227], 14, v[226:227]
	v_lshl_add_u64 v[228:229], s[12:13], 0, v[228:229]
	v_lshlrev_b64 v[224:225], 2, v[224:225]
	v_lshl_add_u64 v[226:227], s[12:13], 0, v[226:227]
	v_lshl_add_u64 v[228:229], v[228:229], 0, v[224:225]
	v_lshl_add_u64 v[230:231], v[226:227], 0, v[224:225]
	global_load_dwordx4 v[232:235], v[228:229], off
	s_nop 0
	global_load_dwordx4 v[236:239], v[230:231], off
	s_waitcnt vmcnt(2)
	s_branch .Linitpf_join_3

; DI void transpose_job(const int TID, const int BID, LAS unsigned char* lds, const float* W, int K, int Nsrc, int Npad, bf16_t* Bt, int mode, const float* kscale) {
;     ...
; #pragma unroll
;         for (int e = 0; e < 4; ++e) tl[(4 * dq + e) * 33 + kp] = pk_bf16(va[e], vb[e]);
;         __syncthreads();
;         {
;             const int n2 = tid >> 3, c2 = tid & 7;
;             u32x4 o;
; #pragma unroll
;             for (int i = 0; i < 4; ++i) o[i] = tl[n2 * 33 + c2 * 4 + i];
;             *(u32x4*)(Bt + (size_t)(n0 + n2) * K + k0 + c2 * 8) = o;
;         }
;         __syncthreads();
.Linitpf_join_3:
	s_sub_i32 s5, s5, s6
	s_sub_i32 s7, s7, s4
	v_readlane_b32 s8, v255, 40
	v_readlane_b32 s9, v255, 41
.LBB0_838:
	s_waitcnt vmcnt(2)
	v_cvt_pk_bf16_f32 v0, v0, v4
	v_cvt_pk_bf16_f32 v1, v1, v5
	ds_write2_b32 v9, v0, v1 offset1:33
	v_cvt_pk_bf16_f32 v0, v2, v6
	v_cvt_pk_bf16_f32 v1, v3, v7
	v_add_u32_e32 v4, s8, v13
	ds_write2_b32 v9, v0, v1 offset0:66 offset1:99
	s_waitcnt lgkmcnt(0)
	s_barrier
	ds_read2_b32 v[0:1], v17 offset1:1
	ds_read2_b32 v[2:3], v17 offset0:2 offset1:3
	v_ashrrev_i32_e32 v5, 31, v4
	s_add_i32 s10, s5, s9
	v_lshlrev_b64 v[4:5], 11, v[4:5]
	v_lshl_add_u64 v[4:5], s[26:27], 0, v[4:5]
	s_ashr_i32 s11, s10, 31
	v_lshl_add_u64 v[4:5], s[10:11], 1, v[4:5]
	s_add_i32 s7, s7, s4
	s_add_i32 s5, s5, s6
	v_lshl_add_u64 v[4:5], v[4:5], 0, v[168:169]
	s_cmpk_lt_i32 s7, 0x400
	s_waitcnt lgkmcnt(0)
	global_store_dwordx4 v[4:5], v[0:3], off
	s_barrier
	s_cbranch_scc0 .LBB0_841

; DI int srccol(int mode, int nidx) {
;     ...
;     if (mode == MODE_GQA) {
;         const int tile = nidx >> 8, tc = nidx & 255, bj = tc >> 7, wc = (tc >> 5) & 3, n = rho >> 4, fq = (rho >> 2) & 3, j = rho & 3;
;         return 64 * (4 * tile + wc) + 32 * (fq >> 1) + 8 * (fq & 1) + 16 * bj + 4 * n + j;
;     }
; DI void transpose_job(const int TID, const int BID, LAS unsigned char* lds, const float* W, int K, int Nsrc, int Npad, bf16_t* Bt, int mode, const float* kscale) {
;     ...
;     for (int t = BID; t < ntile; t += gridDim.x) {
;         const int n0 = (t / nkt) << 6, k0 = (t % nkt) << 6;
;         const int sc = srccol(mode, n0 + 4 * dq);
;         f32x4 va = {0.f, 0.f, 0.f, 0.f}, vb = va;
;         if (sc >= 0) {
;             va = *(const f32x4*)(W + (size_t)(k0 + 2 * kp) * Nsrc + sc); vb = *(const f32x4*)(W + (size_t)(k0 + 2 * kp + 1) * Nsrc + sc);
.LBB0_863:
	s_and_b32 s21, s19, 0x7fffff00
	v_or_b32_e32 v0, s19, v79
	s_lshr_b32 s22, s19, 3
	v_lshlrev_b32_e32 v0, 1, v0
	v_or_b32_e32 v1, s21, v21
	s_add_i32 s21, s20, s16
	v_and_b32_e32 v0, 0xc0, v0
	v_and_or_b32 v1, s22, 16, v1
	v_add_u32_e32 v6, s21, v11
	v_mov_b64_e32 v[2:3], s[0:1]
	v_or3_b32 v0, v1, v0, v17
	v_mad_i64_i32 v[4:5], s[22:23], v6, s95, v[2:3]
	v_mov_b32_e32 v1, v169
	v_add_u32_e32 v6, 1, v6
	v_lshlrev_b64 v[0:1], 2, v[0:1]
	v_mad_i64_i32 v[2:3], s[22:23], v6, s95, v[2:3]
	v_lshl_add_u64 v[4:5], v[4:5], 0, v[0:1]
	v_lshl_add_u64 v[6:7], v[2:3], 0, v[0:1]
	global_load_dwordx4 v[0:3], v[4:5], off
	s_nop 0
	global_load_dwordx4 v[4:7], v[6:7], off
	v_writelane_b32 v255, s19, 40
	v_writelane_b32 v255, s20, 41
	s_add_i32 s16, s16, s17
	s_add_i32 s18, s18, s15
	s_cmpk_ge_i32 s18, 0x180
	s_cbranch_scc1 .Linitpf_skip_4
	s_ashr_i32 s19, s18, 31
	s_lshr_b32 s19, s19, 28
	s_add_i32 s19, s18, s19
	s_ashr_i32 s20, s19, 4
	s_lshl_b32 s19, s20, 6
	s_lshl_b32 s20, s20, 10
	s_sub_i32 s20, 0, s20
	s_cmp_lt_i32 s19, 0
	s_cbranch_scc1 .Linitpf_skip_4
	s_and_b32 s21, s19, 0x7fffff00
	v_or_b32_e32 v224, s19, v79
	s_lshr_b32 s22, s19, 3
	v_lshlrev_b32_e32 v224, 1, v224
	v_or_b32_e32 v225, s21, v21
	s_add_i32 s21, s20, s16
	v_and_b32_e32 v224, 0xc0, v224
	v_and_or_b32 v225, s22, 16, v225
	v_add_u32_e32 v230, s21, v11
	v_mov_b64_e32 v[226:227], s[0:1]
	v_or3_b32 v224, v225, v224, v17
	v_mad_i64_i32 v[228:229], s[22:23], v230, s95, v[226:227]
	v_mov_b32_e32 v225, v169
	v_add_u32_e32 v230, 1, v230
	v_lshlrev_b64 v[224:225], 2, v[224:225]
	v_mad_i64_i32 v[226:227], s[22:23], v230, s95, v[226:227]
	v_lshl_add_u64 v[228:229], v[228:229], 0, v[224:225]
	v_lshl_add_u64 v[230:231], v[226:227], 0, v[224:225]
	global_load_dwordx4 v[232:235], v[228:229], off
	s_nop 0
	global_load_dwordx4 v[236:239], v[230:231], off
	s_waitcnt vmcnt(2)
	s_branch .Linitpf_join_4

; DI void transpose_job(const int TID, const int BID, LAS unsigned char* lds, const float* W, int K, int Nsrc, int Npad, bf16_t* Bt, int mode, const float* kscale) {
;     ...
; #pragma unroll
;         for (int e = 0; e < 4; ++e) tl[(4 * dq + e) * 33 + kp] = pk_bf16(va[e], vb[e]);
;         __syncthreads();
;         {
;             const int n2 = tid >> 3, c2 = tid & 7;
;             u32x4 o;
; #pragma unroll
;             for (int i = 0; i < 4; ++i) o[i] = tl[n2 * 33 + c2 * 4 + i];
;             *(u32x4*)(Bt + (size_t)(n0 + n2) * K + k0 + c2 * 8) = o;
;         }
;         __syncthreads();
.Linitpf_join_4:
	s_sub_i32 s16, s16, s17
	s_sub_i32 s18, s18, s15
	v_readlane_b32 s19, v255, 40
	v_readlane_b32 s20, v255, 41
	s_mov_b32 s22, 0x358637bd
.LBB0_864:
	s_waitcnt vmcnt(2)
	v_cvt_pk_bf16_f32 v0, v0, v4
	v_add_u32_e32 v4, v12, v16
	v_cvt_pk_bf16_f32 v1, v1, v5
	ds_write2_b32 v4, v0, v1 offset1:33
	v_cvt_pk_bf16_f32 v0, v2, v6
	v_cvt_pk_bf16_f32 v1, v3, v7
	ds_write2_b32 v4, v0, v1 offset0:66 offset1:99
	v_add_u32_e32 v2, v14, v15
	v_add_u32_e32 v4, s19, v13
	s_waitcnt lgkmcnt(0)
	s_barrier
	ds_read2_b32 v[0:1], v2 offset1:1
	ds_read2_b32 v[2:3], v2 offset0:2 offset1:3
	v_ashrrev_i32_e32 v5, 31, v4
	s_add_i32 s20, s16, s20
	v_lshlrev_b64 v[4:5], 11, v[4:5]
	v_lshl_add_u64 v[4:5], s[52:53], 0, v[4:5]
	s_ashr_i32 s21, s20, 31
	v_lshl_add_u64 v[4:5], s[20:21], 1, v[4:5]
	s_add_i32 s18, s18, s15
	s_add_i32 s16, s16, s17
	v_lshl_add_u64 v[4:5], v[4:5], 0, v[168:169]
	s_cmpk_lt_i32 s18, 0x180
	s_waitcnt lgkmcnt(0)
	global_store_dwordx4 v[4:5], v[0:3], off
	s_barrier
	s_cbranch_scc0 .LBB0_867

; DI int srccol(int mode, int nidx) {
;     const int rho = nidx & 31;
;     if (mode == MODE_NAT) return nidx;
;     if (mode == MODE_P8) return (nidx & ~31) + perm32(rho);
; DI void transpose_job(const int TID, const int BID, LAS unsigned char* lds, const float* W, int K, int Nsrc, int Npad, bf16_t* Bt, int mode, const float* kscale) {
;     ...
;     for (int t = BID; t < ntile; t += gridDim.x) {
;         const int n0 = (t / nkt) << 6, k0 = (t % nkt) << 6;
;         const int sc = srccol(mode, n0 + 4 * dq);
;         f32x4 va = {0.f, 0.f, 0.f, 0.f}, vb = va;
;         if (sc >= 0) {
;             va = *(const f32x4*)(W + (size_t)(k0 + 2 * kp) * Nsrc + sc); vb = *(const f32x4*)(W + (size_t)(k0 + 2 * kp + 1) * Nsrc + sc);
.LBB0_869:
	s_add_i32 s21, s20, s16
	v_add_u32_e32 v2, s21, v11
	v_ashrrev_i32_e32 v3, 31, v2
	v_lshlrev_b64 v[4:5], 12, v[2:3]
	v_add_u32_e32 v2, 1, v2
	v_ashrrev_i32_e32 v3, 31, v2
	v_or_b32_e32 v0, s19, v19
	v_mov_b32_e32 v1, v169
	v_lshlrev_b64 v[2:3], 12, v[2:3]
	v_lshl_add_u64 v[4:5], s[54:55], 0, v[4:5]
	v_lshlrev_b64 v[0:1], 2, v[0:1]
	v_lshl_add_u64 v[2:3], s[54:55], 0, v[2:3]
	v_lshl_add_u64 v[4:5], v[4:5], 0, v[0:1]
	v_lshl_add_u64 v[6:7], v[2:3], 0, v[0:1]
	global_load_dwordx4 v[0:3], v[4:5], off
	s_nop 0
	global_load_dwordx4 v[4:7], v[6:7], off
	v_writelane_b32 v255, s19, 40
	v_writelane_b32 v255, s20, 41
	s_add_i32 s16, s16, s17
	s_add_i32 s18, s18, s15
	s_cmpk_ge_i32 s18, 0x100
	s_cbranch_scc1 .Linitpf_skip_5
	s_ashr_i32 s19, s18, 31
	s_lshr_b32 s19, s19, 28
	s_add_i32 s19, s18, s19
	s_ashr_i32 s20, s19, 4
	s_lshl_b32 s19, s20, 6
	s_lshl_b32 s20, s20, 10
	s_sub_i32 s20, 0, s20
	s_cmp_lt_i32 s19, 0
	s_cbranch_scc1 .Linitpf_skip_5
	s_add_i32 s21, s20, s16
	v_add_u32_e32 v226, s21, v11
	v_ashrrev_i32_e32 v227, 31, v226
	v_lshlrev_b64 v[228:229], 12, v[226:227]
	v_add_u32_e32 v226, 1, v226
	v_ashrrev_i32_e32 v227, 31, v226
	v_or_b32_e32 v224, s19, v19
	v_mov_b32_e32 v225, v169
	v_lshlrev_b64 v[226:227], 12, v[226:227]
	v_lshl_add_u64 v[228:229], s[54:55], 0, v[228:229]
	v_lshlrev_b64 v[224:225], 2, v[224:225]
	v_lshl_add_u64 v[226:227], s[54:55], 0, v[226:227]
	v_lshl_add_u64 v[228:229], v[228:229], 0, v[224:225]
	v_lshl_add_u64 v[230:231], v[226:227], 0, v[224:225]
	global_load_dwordx4 v[232:235], v[228:229], off
	s_nop 0
	global_load_dwordx4 v[236:239], v[230:231], off
	s_waitcnt vmcnt(2)
	s_branch .Linitpf_join_5

; DI void transpose_job(const int TID, const int BID, LAS unsigned char* lds, const float* W, int K, int Nsrc, int Npad, bf16_t* Bt, int mode, const float* kscale) {
;     ...
; #pragma unroll
;         for (int e = 0; e < 4; ++e) tl[(4 * dq + e) * 33 + kp] = pk_bf16(va[e], vb[e]);
;         __syncthreads();
;         {
;             const int n2 = tid >> 3, c2 = tid & 7;
;             u32x4 o;
; #pragma unroll
;             for (int i = 0; i < 4; ++i) o[i] = tl[n2 * 33 + c2 * 4 + i];
;             *(u32x4*)(Bt + (size_t)(n0 + n2) * K + k0 + c2 * 8) = o;
;         }
;         __syncthreads();
.Linitpf_join_5:
	s_sub_i32 s16, s16, s17
	s_sub_i32 s18, s18, s15
	v_readlane_b32 s19, v255, 40
	v_readlane_b32 s20, v255, 41
.LBB0_870:
	s_waitcnt vmcnt(2)
	v_cvt_pk_bf16_f32 v0, v0, v4
	v_add_u32_e32 v4, v12, v16
	v_cvt_pk_bf16_f32 v1, v1, v5
	ds_write2_b32 v4, v0, v1 offset1:33
	v_cvt_pk_bf16_f32 v0, v2, v6
	v_cvt_pk_bf16_f32 v1, v3, v7
	ds_write2_b32 v4, v0, v1 offset0:66 offset1:99
	v_add_u32_e32 v2, v14, v15
	v_add_u32_e32 v4, s19, v13
	s_waitcnt lgkmcnt(0)
	s_barrier
	ds_read2_b32 v[0:1], v2 offset1:1
	ds_read2_b32 v[2:3], v2 offset0:2 offset1:3
	v_ashrrev_i32_e32 v5, 31, v4
	s_add_i32 s20, s16, s20
	v_lshlrev_b64 v[4:5], 11, v[4:5]
	v_lshl_add_u64 v[4:5], s[56:57], 0, v[4:5]
	s_ashr_i32 s21, s20, 31
	v_lshl_add_u64 v[4:5], s[20:21], 1, v[4:5]
	s_add_i32 s18, s18, s15
	s_add_i32 s16, s16, s17
	v_lshl_add_u64 v[4:5], v[4:5], 0, v[168:169]
	s_cmpk_lt_i32 s18, 0x100
	s_waitcnt lgkmcnt(0)
	global_store_dwordx4 v[4:5], v[0:3], off
	s_barrier
	s_cbranch_scc0 .LBB0_873

; DI int srccol(int mode, int nidx) {
;     const int rho = nidx & 31;
;     if (mode == MODE_NAT) return nidx;
;     if (mode == MODE_P8) return (nidx & ~31) + perm32(rho);
; DI void transpose_job(const int TID, const int BID, LAS unsigned char* lds, const float* W, int K, int Nsrc, int Npad, bf16_t* Bt, int mode, const float* kscale) {
;     ...
;     for (int t = BID; t < ntile; t += gridDim.x) {
;         const int n0 = (t / nkt) << 6, k0 = (t % nkt) << 6;
;         const int sc = srccol(mode, n0 + 4 * dq);
;         f32x4 va = {0.f, 0.f, 0.f, 0.f}, vb = va;
;         if (sc >= 0) {
;             va = *(const f32x4*)(W + (size_t)(k0 + 2 * kp) * Nsrc + sc); vb = *(const f32x4*)(W + (size_t)(k0 + 2 * kp + 1) * Nsrc + sc);
.LBB0_896:
	s_add_i32 s21, s20, s16
	v_add_u32_e32 v2, s21, v11
	v_ashrrev_i32_e32 v3, 31, v2
	v_lshlrev_b64 v[4:5], 12, v[2:3]
	v_add_u32_e32 v2, 1, v2
	v_ashrrev_i32_e32 v3, 31, v2
	v_or_b32_e32 v0, s19, v19
	v_mov_b32_e32 v1, v169
	v_lshlrev_b64 v[2:3], 12, v[2:3]
	v_lshl_add_u64 v[4:5], s[0:1], 0, v[4:5]
	v_lshlrev_b64 v[0:1], 2, v[0:1]
	v_lshl_add_u64 v[2:3], s[0:1], 0, v[2:3]
	v_lshl_add_u64 v[4:5], v[4:5], 0, v[0:1]
	v_lshl_add_u64 v[6:7], v[2:3], 0, v[0:1]
	global_load_dwordx4 v[0:3], v[4:5], off
	s_nop 0
	global_load_dwordx4 v[4:7], v[6:7], off
	v_writelane_b32 v255, s19, 40
	v_writelane_b32 v255, s20, 41
	s_add_i32 s16, s16, s17
	s_add_i32 s18, s18, s15
	s_cmpk_ge_i32 s18, 0x100
	s_cbranch_scc1 .Linitpf_skip_6
	s_ashr_i32 s19, s18, 31
	s_lshr_b32 s19, s19, 28
	s_add_i32 s19, s18, s19
	s_ashr_i32 s20, s19, 4
	s_lshl_b32 s19, s20, 6
	s_lshl_b32 s20, s20, 10
	s_sub_i32 s20, 0, s20
	s_cmp_lt_i32 s19, 0
	s_cbranch_scc1 .Linitpf_skip_6
	s_add_i32 s21, s20, s16
	v_add_u32_e32 v226, s21, v11
	v_ashrrev_i32_e32 v227, 31, v226
	v_lshlrev_b64 v[228:229], 12, v[226:227]
	v_add_u32_e32 v226, 1, v226
	v_ashrrev_i32_e32 v227, 31, v226
	v_or_b32_e32 v224, s19, v19
	v_mov_b32_e32 v225, v169
	v_lshlrev_b64 v[226:227], 12, v[226:227]
	v_lshl_add_u64 v[228:229], s[0:1], 0, v[228:229]
	v_lshlrev_b64 v[224:225], 2, v[224:225]
	v_lshl_add_u64 v[226:227], s[0:1], 0, v[226:227]
	v_lshl_add_u64 v[228:229], v[228:229], 0, v[224:225]
	v_lshl_add_u64 v[230:231], v[226:227], 0, v[224:225]
	global_load_dwordx4 v[232:235], v[228:229], off
	s_nop 0
	global_load_dwordx4 v[236:239], v[230:231], off
	s_waitcnt vmcnt(2)
	s_branch .Linitpf_join_6

; DI void transpose_job(const int TID, const int BID, LAS unsigned char* lds, const float* W, int K, int Nsrc, int Npad, bf16_t* Bt, int mode, const float* kscale) {
;     ...
; #pragma unroll
;         for (int e = 0; e < 4; ++e) tl[(4 * dq + e) * 33 + kp] = pk_bf16(va[e], vb[e]);
;         __syncthreads();
;         {
;             const int n2 = tid >> 3, c2 = tid & 7;
;             u32x4 o;
; #pragma unroll
;             for (int i = 0; i < 4; ++i) o[i] = tl[n2 * 33 + c2 * 4 + i];
;             *(u32x4*)(Bt + (size_t)(n0 + n2) * K + k0 + c2 * 8) = o;
;         }
;         __syncthreads();
;     }
.LBB0_897:
	s_waitcnt vmcnt(2)
	v_cvt_pk_bf16_f32 v0, v0, v4
	v_add_u32_e32 v4, v12, v16
	v_cvt_pk_bf16_f32 v1, v1, v5
	ds_write2_b32 v4, v0, v1 offset1:33
	v_cvt_pk_bf16_f32 v0, v2, v6
	v_cvt_pk_bf16_f32 v1, v3, v7
	ds_write2_b32 v4, v0, v1 offset0:66 offset1:99
	v_add_u32_e32 v2, v14, v15
	v_add_u32_e32 v4, s19, v13
	s_waitcnt lgkmcnt(0)
	s_barrier
	ds_read2_b32 v[0:1], v2 offset1:1
	ds_read2_b32 v[2:3], v2 offset0:2 offset1:3
	v_ashrrev_i32_e32 v5, 31, v4
	s_add_i32 s20, s16, s20
	v_lshlrev_b64 v[4:5], 11, v[4:5]
	v_lshl_add_u64 v[4:5], s[52:53], 0, v[4:5]
	s_ashr_i32 s21, s20, 31
	v_lshl_add_u64 v[4:5], s[20:21], 1, v[4:5]
	s_add_i32 s18, s18, s15
	s_add_i32 s16, s16, s17
	v_lshl_add_u64 v[4:5], v[4:5], 0, v[168:169]
	s_cmpk_lt_i32 s18, 0x100
	s_waitcnt lgkmcnt(0)
	global_store_dwordx4 v[4:5], v[0:3], off
	s_barrier
	s_cbranch_scc0 .LBB0_860
